# NA loop: relative-position-bias gathered with 16 unconditional LDS reads issued together instead of 16 serialized exec-masked read-wait-add blocks
# speedup vs baseline: 1.0048x; 1.0048x over previous
; #define MFMA(a, b, c) __builtin_amdgcn_mfma_f32_32x32x16_bf16((a), (b), (c), 0, 0, 0)
; DI float fexp2(float x) { return __builtin_amdgcn_exp2f(x); }
; DI void flash_pass_na(f32x16 (&o)[2], const u16* __restrict__ Qp, const u16* __restrict__ Kb, int ldk,
;                       const u16* __restrict__ Vt, int S, int tile0, int ntiles, char* lds, int wlo, int whi,
;                       const float* bias_lds, int qrow, int rs_q, int qcol, int cs0) {
;     ...
;     if (kr >= wlo && kr <= whi) {
;       f32x16 s0;
; #pragma unroll
;       for (int i = 0; i < 16; ++i) s0[i] = 0.f;
;       {
;         bf16x8 ka[4];
; #pragma unroll
;         for (int ks = 0; ks < 4; ++ks) ka[ks] = *(const bf16x8*)(st + krow * 128 + (((2 * ks + h) ^ ksw) << 4));
;         asm volatile("" ::: "memory");
; #pragma unroll
;         for (int ks = 0; ks < 4; ++ks) s0 = MFMA(ka[ks], q[ks], s0);
;       }
;       bf16x8 vf[2][2];
; #pragma unroll
;       for (int c2 = 0; c2 < 2; ++c2) {
;         const int co = ((vch0 + 2 * c2 + h) ^ vsw) << 4;
; #pragma unroll
;         for (int mv = 0; mv < 2; ++mv) vf[c2][mv] = *(const bf16x8*)(st + 8192 + (mv * 32 + r) * 128 + co);
;       }
;       asm volatile("" ::: "memory");
;       const bool rowok = (kr >= rs_q) && (kr <= rs_q + 7);
;       const int bidx = rowok ? ((kr - qrow + 7) * 31 + dcb) : 64;
;       float t[16];
; #pragma unroll
;       for (int i = 0; i < 16; ++i) {
;         const int j = i >> 2;
;         const int kco = 16 * (j >> 1) + 4 * (j & 1) + (i & 3);
;         const bool ok = navalid[i] && rowok;
;         const float bv = bias_lds[ok ? (bidx + kco) : 0];
;         t[i] = ok ? (s0[i] + bv) : -INFINITY;
;       }
;       float mx = t[0];
; #pragma unroll
;       for (int e = 1; e < 16; ++e) mx = fmaxf(mx, t[e]);
;       mx = fmaxf(mx, __shfl_xor(mx, 32));
;       if (__builtin_amdgcn_ballot_w64(mx > m_run + 8.f) != 0ull) {
;         const float m_new = fmaxf(m_run, mx);
;         const float alpha = fexp2(m_run - m_new);
;         l_run *= alpha;
;         m_run = m_new;
; #pragma unroll
;         for (int mv = 0; mv < 2; ++mv)
; #pragma unroll
;           for (int i = 0; i < 16; ++i) o[mv][i] *= alpha;
;       }
.LBB0_119:
	s_add_i32 s70, s65, s69
	v_cmp_ge_u32_e32 vcc, s70, v115
	v_cmp_le_u32_e64 s[46:47], s70, v116
	s_and_b64 s[46:47], vcc, s[46:47]
	s_and_saveexec_b64 s[10:11], s[46:47]
	s_cbranch_execz .LBB0_155
	s_bitcmp1_b32 s69, 0
	s_cselect_b32 s46, 0x6000, 0
	v_add_u32_e32 v78, s46, v117
	v_add_u32_e32 v34, v78, v120
	ds_read_b128 v[34:37], v34
	v_add_u32_e32 v38, v78, v121
	ds_read_b128 v[74:77], v38
	v_add_u32_e32 v79, v78, v122
	v_add_u32_e32 v78, v78, v123
	ds_read_b128 v[128:131], v78
	v_or_b32_e32 v80, s46, v125
	v_cmp_ge_u32_e32 vcc, s70, v114
	s_waitcnt lgkmcnt(2)
	v_mfma_f32_32x32x16_bf16 v[34:49], v[34:37], v[50:53], 0
	s_waitcnt lgkmcnt(1)
	v_mfma_f32_32x32x16_bf16 v[34:49], v[74:77], v[54:57], v[34:49]
	ds_read_b128 v[74:77], v79
	v_or_b32_e32 v79, s46, v124
	v_add_u32_e32 v79, v79, v118
	v_cmp_le_u32_e64 s[46:47], s70, v119
	s_and_b64 vcc, vcc, s[46:47]
	s_and_b64 s[70:71], s[12:13], vcc
	s_waitcnt lgkmcnt(0)
	v_mfma_f32_32x32x16_bf16 v[34:49], v[74:77], v[58:61], v[34:49]
	v_add_u32_e32 v74, v80, v118
	ds_read_b128 v[86:89], v79 offset:8192
	ds_read_b128 v[82:85], v79 offset:12288
	ds_read_b128 v[78:81], v74 offset:8192
	ds_read_b128 v[74:77], v74 offset:12288
	v_mfma_f32_32x32x16_bf16 v[34:49], v[128:131], v[62:65], v[34:49]
	v_cndmask_b32_e32 v128, 64, v126, vcc
	v_lshlrev_b32_e32 v132, 2, v128
	v_mov_b32_e32 v133, 0xff800000
	ds_read_b32 v134, v132 offset:49152
	ds_read_b32 v135, v132 offset:49156
	ds_read_b32 v136, v132 offset:49160
	ds_read_b32 v137, v132 offset:49164
	ds_read_b32 v138, v132 offset:49168
	ds_read_b32 v139, v132 offset:49172
	ds_read_b32 v140, v132 offset:49176
	ds_read_b32 v141, v132 offset:49180
	ds_read_b32 v142, v132 offset:49216
	ds_read_b32 v143, v132 offset:49220
	ds_read_b32 v144, v132 offset:49224
	ds_read_b32 v145, v132 offset:49228
	ds_read_b32 v146, v132 offset:49232
	ds_read_b32 v147, v132 offset:49236
	ds_read_b32 v148, v132 offset:49240
	ds_read_b32 v149, v132 offset:49244
	s_waitcnt lgkmcnt(0)
	s_and_b64 s[70:71], s[12:13], vcc
	v_add_f32_e32 v129, v34, v134
	v_cndmask_b32_e64 v129, v133, v129, s[70:71]
	s_and_b64 s[70:71], s[14:15], vcc
	v_add_f32_e32 v128, v35, v135
	v_cndmask_b32_e64 v128, v133, v128, s[70:71]
	s_and_b64 s[70:71], s[16:17], vcc
	v_add_f32_e32 v35, v36, v136
	v_cndmask_b32_e64 v35, v133, v35, s[70:71]
	s_and_b64 s[70:71], s[18:19], vcc
	v_add_f32_e32 v34, v37, v137
	v_cndmask_b32_e64 v34, v133, v34, s[70:71]
	s_and_b64 s[70:71], s[20:21], vcc
	v_add_f32_e32 v37, v38, v138
	v_cndmask_b32_e64 v37, v133, v37, s[70:71]
	s_and_b64 s[70:71], s[22:23], vcc
	v_add_f32_e32 v36, v39, v139
	v_cndmask_b32_e64 v36, v133, v36, s[70:71]
	s_and_b64 s[70:71], s[24:25], vcc
	v_add_f32_e32 v130, v40, v140
	v_cndmask_b32_e64 v130, v133, v130, s[70:71]
	s_and_b64 s[70:71], s[26:27], vcc
	v_add_f32_e32 v38, v41, v141
	v_cndmask_b32_e64 v38, v133, v38, s[70:71]
	s_and_b64 s[70:71], s[28:29], vcc
	v_add_f32_e32 v41, v42, v142
	v_cndmask_b32_e64 v41, v133, v41, s[70:71]
	s_and_b64 s[70:71], s[30:31], vcc
	v_add_f32_e32 v40, v43, v143
	v_cndmask_b32_e64 v40, v133, v40, s[70:71]
	s_and_b64 s[70:71], s[34:35], vcc
	v_add_f32_e32 v131, v44, v144
	v_cndmask_b32_e64 v131, v133, v131, s[70:71]
	s_and_b64 s[70:71], s[36:37], vcc
	v_add_f32_e32 v39, v45, v145
	v_cndmask_b32_e64 v39, v133, v39, s[70:71]
	s_and_b64 s[70:71], s[38:39], vcc
	v_add_f32_e32 v43, v46, v146
	v_cndmask_b32_e64 v43, v133, v43, s[70:71]
	s_and_b64 s[70:71], s[40:41], vcc
	v_add_f32_e32 v42, v47, v147
	v_cndmask_b32_e64 v42, v133, v42, s[70:71]
	s_and_b64 s[70:71], s[42:43], vcc
	v_add_f32_e32 v45, v48, v148
	v_cndmask_b32_e64 v45, v133, v45, s[70:71]
	s_and_b64 s[70:71], s[44:45], vcc
	v_add_f32_e32 v44, v49, v149
	v_cndmask_b32_e64 v44, v133, v44, s[70:71]
	v_max_f32_e32 v46, v128, v128
	v_max_f32_e32 v47, v129, v129
	v_max_f32_e32 v46, v47, v46
	v_max3_f32 v46, v46, v35, v34
	v_max3_f32 v46, v46, v37, v36
	v_max3_f32 v46, v46, v130, v38
	v_max3_f32 v46, v46, v41, v40
	v_max3_f32 v46, v46, v131, v39
	v_cmp_lt_i32_e32 vcc, v214, v208
	v_max3_f32 v46, v46, v43, v42
	v_max3_f32 v46, v46, v45, v44
	v_cndmask_b32_e32 v47, v207, v214, vcc
	v_lshlrev_b32_e32 v47, 2, v47
	ds_bpermute_b32 v47, v47, v46
	s_waitcnt lgkmcnt(0)
	v_max_f32_e32 v47, v47, v47
	v_max_f32_e32 v46, v46, v47
	v_add_f32_e32 v47, 0x41000000, v127
	v_cmp_gt_f32_e32 vcc, v46, v47
	s_cbranch_vccz .LBB0_154
	v_max_f32_e32 v46, v46, v46
	v_max_f32_e32 v47, v127, v127
	v_max_f32_e32 v47, v47, v46
	v_sub_f32_e32 v46, v127, v47
	v_exp_f32_e32 v46, v46
	v_mov_b32_e32 v127, v47
	v_pk_mul_f32 v[16:17], v[16:17], v[46:47] op_sel_hi:[1,0]
	v_pk_mul_f32 v[14:15], v[14:15], v[46:47] op_sel_hi:[1,0]
	v_pk_mul_f32 v[12:13], v[12:13], v[46:47] op_sel_hi:[1,0]
	v_pk_mul_f32 v[10:11], v[10:11], v[46:47] op_sel_hi:[1,0]
	v_pk_mul_f32 v[8:9], v[8:9], v[46:47] op_sel_hi:[1,0]
	v_pk_mul_f32 v[6:7], v[6:7], v[46:47] op_sel_hi:[1,0]
	v_pk_mul_f32 v[4:5], v[4:5], v[46:47] op_sel_hi:[1,0]
	v_pk_mul_f32 v[2:3], v[2:3], v[46:47] op_sel_hi:[1,0]
	v_pk_mul_f32 v[32:33], v[32:33], v[46:47] op_sel_hi:[1,0]
	v_pk_mul_f32 v[30:31], v[30:31], v[46:47] op_sel_hi:[1,0]
	v_pk_mul_f32 v[28:29], v[28:29], v[46:47] op_sel_hi:[1,0]
	v_pk_mul_f32 v[26:27], v[26:27], v[46:47] op_sel_hi:[1,0]
	v_pk_mul_f32 v[24:25], v[24:25], v[46:47] op_sel_hi:[1,0]
	v_pk_mul_f32 v[22:23], v[22:23], v[46:47] op_sel_hi:[1,0]
	v_pk_mul_f32 v[20:21], v[20:21], v[46:47] op_sel_hi:[1,0]
	v_pk_mul_f32 v[18:19], v[18:19], v[46:47] op_sel_hi:[1,0]
	v_mul_f32_e32 v0, v0, v46
